# XCD-local barriers: waiting workgroups issue their L1 invalidate right after arriving (overlaps the wait) instead of after the release
# speedup vs baseline: 1.0292x; 1.0099x over previous
; __device__ __forceinline__ unsigned xb_ld(unsigned* p)              { return __hip_atomic_load(p, __ATOMIC_RELAXED, __HIP_MEMORY_SCOPE_AGENT); }
; __device__ __forceinline__ unsigned xb_add(unsigned* p, unsigned v) { return __hip_atomic_fetch_add(p, v, __ATOMIC_RELAXED, __HIP_MEMORY_SCOPE_AGENT); }
; #define XB_SPIN(cond, bar) do { unsigned _sp = 0; while (cond) { __builtin_amdgcn_s_sleep(1); \
;     if ((++_sp & 255u) == 0u) { if (xb_ld(&(bar)[XB_TMO])) break; if (_sp > XB_SPIN_CAP) { atomicAdd(&(bar)[XB_TMO], 1u); break; } } } } while (0)
; __device__ __forceinline__ void xcd_barrier(const XcdBarrier& b) {
;     ...
;         unsigned nloc = b.st[0], nx = b.st[1];
;         if (nloc == 0u) { xcd_barrier_complete(bar, b.x, nloc, nx); b.st[0] = nloc; b.st[1] = nx; }
;         const unsigned old = xb_add(&bar[XB_XSUB(b.x)], 1u);
;         const unsigned gen = old / nloc;
;         if (old + 1u == (gen + 1u) * nloc) {
;             __builtin_amdgcn_fence(__ATOMIC_RELEASE, "agent");
;             asm volatile("s_waitcnt vmcnt(0)" ::: "memory");
;             const unsigned og = xb_add(&bar[XB_TOP], 1u);
;             const unsigned tg = og / nx;
;             if (og + 1u == (tg + 1u) * nx) xb_add(&bar[XB_TOPGEN], 1u);
;             else XB_SPIN(xb_ld(&bar[XB_TOPGEN]) == tg, bar);
;             __builtin_amdgcn_fence(__ATOMIC_ACQUIRE, "agent");
;             xb_add(&bar[XB_XGEN(b.x)], 1u);
;             asm volatile("s_waitcnt vmcnt(0)" ::: "memory");
;         } else {
;             XB_SPIN(xb_ld(&bar[XB_XGEN(b.x)]) == gen, bar);
;             __builtin_amdgcn_fence(__ATOMIC_ACQUIRE, "agent");
;             asm volatile("s_waitcnt vmcnt(0)" ::: "memory");
;         }
.LBB0_106:
	s_or_b64 exec, exec, s[10:11]
	v_cvt_f32_u32_e32 v4, v2
	s_waitcnt vmcnt(0)
	v_readfirstlane_b32 s6, v3
	v_sub_u32_e32 v3, 0, v2
	v_rcp_iflag_f32_e32 v4, v4
	v_add_u32_e32 v5, s6, v1
	v_mul_f32_e32 v4, 0x4f7ffffe, v4
	v_cvt_u32_f32_e32 v4, v4
	v_mul_lo_u32 v1, v3, v4
	v_mul_hi_u32 v1, v4, v1
	v_add_u32_e32 v1, v4, v1
	v_mul_hi_u32 v1, v5, v1
	v_mul_lo_u32 v3, v1, v2
	v_sub_u32_e32 v3, v5, v3
	v_add_u32_e32 v4, 1, v1
	v_cmp_ge_u32_e32 vcc, v3, v2
	s_nop 1
	v_cndmask_b32_e32 v1, v1, v4, vcc
	v_sub_u32_e32 v4, v3, v2
	v_cndmask_b32_e32 v3, v3, v4, vcc
	v_add_u32_e32 v4, 1, v1
	v_cmp_ge_u32_e32 vcc, v3, v2
	v_add_u32_e32 v3, 1, v5
	s_nop 0
	v_cndmask_b32_e32 v1, v1, v4, vcc
	v_mul_lo_u32 v4, v2, v1
	v_add_u32_e32 v2, v4, v2
	v_cmp_ne_u32_e32 vcc, v3, v2
	s_and_saveexec_b64 s[6:7], vcc
	s_xor_b64 s[6:7], exec, s[6:7]
	s_cbranch_execz .LBB0_120
	s_waitcnt lgkmcnt(0)
	v_readlane_b32 s100, v244, 61
	s_cmp_eq_u32 s100, 0
	s_cbranch_scc1 .Lei_a1
	buffer_inv sc1
.Lei_a1:
	v_mov_b32_e32 v0, 0x2000
	global_load_dword v0, v0, s[4:5] offset:1024 sc1
	s_add_u32 s20, s4, 0x2400
	s_addc_u32 s21, s5, 0
	s_waitcnt vmcnt(0)
	v_cmp_eq_u32_e32 vcc, v0, v1
	s_and_saveexec_b64 s[10:11], vcc
	s_cbranch_execz .LBB0_119
	s_add_u32 s16, s92, 0xc0200
	s_addc_u32 s17, s93, 0
	s_mov_b32 s33, 1
	s_mov_b64 s[22:23], 0
	v_mov_b32_e32 v0, 0
	s_branch .LBB0_110

; __device__ __forceinline__ unsigned xb_ld(unsigned* p)              { return __hip_atomic_load(p, __ATOMIC_RELAXED, __HIP_MEMORY_SCOPE_AGENT); }
; __device__ __forceinline__ unsigned xb_add(unsigned* p, unsigned v) { return __hip_atomic_fetch_add(p, v, __ATOMIC_RELAXED, __HIP_MEMORY_SCOPE_AGENT); }
; #define XB_SPIN(cond, bar) do { unsigned _sp = 0; while (cond) { __builtin_amdgcn_s_sleep(1); \
;     if ((++_sp & 255u) == 0u) { if (xb_ld(&(bar)[XB_TMO])) break; if (_sp > XB_SPIN_CAP) { atomicAdd(&(bar)[XB_TMO], 1u); break; } } } } while (0)
; __device__ __forceinline__ void xcd_barrier(const XcdBarrier& b) {
;     ...
;         const unsigned old = xb_add(&bar[XB_XSUB(b.x)], 1u);
;         const unsigned gen = old / nloc;
;         if (old + 1u == (gen + 1u) * nloc) {
;             __builtin_amdgcn_fence(__ATOMIC_RELEASE, "agent");
;             asm volatile("s_waitcnt vmcnt(0)" ::: "memory");
;             const unsigned og = xb_add(&bar[XB_TOP], 1u);
;             const unsigned tg = og / nx;
;             if (og + 1u == (tg + 1u) * nx) xb_add(&bar[XB_TOPGEN], 1u);
;             else XB_SPIN(xb_ld(&bar[XB_TOPGEN]) == tg, bar);
;             __builtin_amdgcn_fence(__ATOMIC_ACQUIRE, "agent");
;             xb_add(&bar[XB_XGEN(b.x)], 1u);
;             asm volatile("s_waitcnt vmcnt(0)" ::: "memory");
;         } else {
;             XB_SPIN(xb_ld(&bar[XB_XGEN(b.x)]) == gen, bar);
;             __builtin_amdgcn_fence(__ATOMIC_ACQUIRE, "agent");
;             asm volatile("s_waitcnt vmcnt(0)" ::: "memory");
;         }
.LBB0_119:
	s_or_b64 exec, exec, s[10:11]
	s_waitcnt vmcnt(0)
	v_readlane_b32 s100, v244, 61
	s_cmp_lg_u32 s100, 0
	s_cbranch_scc1 .Lei_b1
	buffer_inv sc1
	s_waitcnt vmcnt(0)
.Lei_b1:
.LBB0_120:
	s_andn2_saveexec_b64 s[6:7], s[6:7]
	s_cbranch_execz .LBB0_140
	s_mov_b64 s[6:7], exec
	v_readlane_b32 s100, v244, 61
	s_cmp_lg_u32 s100, 0
	s_cbranch_scc1 .LBB0_137
	buffer_wbl2 sc1
	s_waitcnt lgkmcnt(0)
	s_waitcnt vmcnt(0)
	v_mbcnt_lo_u32_b32 v1, s6, 0
	v_mbcnt_hi_u32_b32 v1, s7, v1
	v_cmp_eq_u32_e32 vcc, 0, v1
	s_and_saveexec_b64 s[10:11], vcc
	s_cbranch_execz .LBB0_123
	s_bcnt1_i32_b64 s6, s[6:7]
	v_mov_b32_e32 v2, 0xc3000
	v_mov_b32_e32 v3, s6
	global_atomic_add v2, v2, v3, s[92:93] offset:1024 sc0

; __device__ __forceinline__ unsigned xb_ld(unsigned* p)              { return __hip_atomic_load(p, __ATOMIC_RELAXED, __HIP_MEMORY_SCOPE_AGENT); }
; __device__ __forceinline__ unsigned xb_add(unsigned* p, unsigned v) { return __hip_atomic_fetch_add(p, v, __ATOMIC_RELAXED, __HIP_MEMORY_SCOPE_AGENT); }
; #define XB_SPIN(cond, bar) do { unsigned _sp = 0; while (cond) { __builtin_amdgcn_s_sleep(1); \
;     if ((++_sp & 255u) == 0u) { if (xb_ld(&(bar)[XB_TMO])) break; if (_sp > XB_SPIN_CAP) { atomicAdd(&(bar)[XB_TMO], 1u); break; } } } } while (0)
; __device__ __forceinline__ void xcd_barrier(const XcdBarrier& b) {
;     ...
;         unsigned nloc = b.st[0], nx = b.st[1];
;         if (nloc == 0u) { xcd_barrier_complete(bar, b.x, nloc, nx); b.st[0] = nloc; b.st[1] = nx; }
;         const unsigned old = xb_add(&bar[XB_XSUB(b.x)], 1u);
;         const unsigned gen = old / nloc;
;         if (old + 1u == (gen + 1u) * nloc) {
;             __builtin_amdgcn_fence(__ATOMIC_RELEASE, "agent");
;             asm volatile("s_waitcnt vmcnt(0)" ::: "memory");
;             const unsigned og = xb_add(&bar[XB_TOP], 1u);
;             const unsigned tg = og / nx;
;             if (og + 1u == (tg + 1u) * nx) xb_add(&bar[XB_TOPGEN], 1u);
;             else XB_SPIN(xb_ld(&bar[XB_TOPGEN]) == tg, bar);
;             __builtin_amdgcn_fence(__ATOMIC_ACQUIRE, "agent");
;             xb_add(&bar[XB_XGEN(b.x)], 1u);
;             asm volatile("s_waitcnt vmcnt(0)" ::: "memory");
;         } else {
;             XB_SPIN(xb_ld(&bar[XB_XGEN(b.x)]) == gen, bar);
;             __builtin_amdgcn_fence(__ATOMIC_ACQUIRE, "agent");
;             asm volatile("s_waitcnt vmcnt(0)" ::: "memory");
;         }
.LBB0_176:
	s_or_b64 exec, exec, s[16:17]
	v_cvt_f32_u32_e32 v4, v2
	s_waitcnt vmcnt(0)
	v_readfirstlane_b32 s10, v3
	v_sub_u32_e32 v3, 0, v2
	v_rcp_iflag_f32_e32 v4, v4
	v_add_u32_e32 v5, s10, v1
	v_mul_f32_e32 v4, 0x4f7ffffe, v4
	v_cvt_u32_f32_e32 v4, v4
	v_mul_lo_u32 v1, v3, v4
	v_mul_hi_u32 v1, v4, v1
	v_add_u32_e32 v1, v4, v1
	v_mul_hi_u32 v1, v5, v1
	v_mul_lo_u32 v3, v1, v2
	v_sub_u32_e32 v3, v5, v3
	v_add_u32_e32 v4, 1, v1
	v_cmp_ge_u32_e32 vcc, v3, v2
	s_nop 1
	v_cndmask_b32_e32 v1, v1, v4, vcc
	v_sub_u32_e32 v4, v3, v2
	v_cndmask_b32_e32 v3, v3, v4, vcc
	v_add_u32_e32 v4, 1, v1
	v_cmp_ge_u32_e32 vcc, v3, v2
	v_add_u32_e32 v3, 1, v5
	s_nop 0
	v_cndmask_b32_e32 v1, v1, v4, vcc
	v_mul_lo_u32 v4, v2, v1
	v_add_u32_e32 v2, v4, v2
	v_cmp_ne_u32_e32 vcc, v3, v2
	s_and_saveexec_b64 s[10:11], vcc
	s_xor_b64 s[10:11], exec, s[10:11]
	s_cbranch_execz .LBB0_190
	s_waitcnt lgkmcnt(0)
	v_readlane_b32 s100, v244, 61
	s_cmp_eq_u32 s100, 0
	s_cbranch_scc1 .Lei_a2
	buffer_inv sc1
.Lei_a2:
	v_mov_b32_e32 v0, 0x2000
	global_load_dword v0, v0, s[6:7] offset:1024 sc1
	s_add_u32 s22, s6, 0x2400
	s_addc_u32 s23, s7, 0
	s_waitcnt vmcnt(0)
	v_cmp_eq_u32_e32 vcc, v0, v1
	s_and_saveexec_b64 s[16:17], vcc
	s_cbranch_execz .LBB0_189
	s_add_u32 s20, s92, 0xc0200
	s_addc_u32 s21, s93, 0
	s_mov_b32 s38, 1
	s_mov_b64 s[24:25], 0
	v_mov_b32_e32 v0, 0
	s_branch .LBB0_180

; __device__ __forceinline__ unsigned xb_ld(unsigned* p)              { return __hip_atomic_load(p, __ATOMIC_RELAXED, __HIP_MEMORY_SCOPE_AGENT); }
; __device__ __forceinline__ unsigned xb_add(unsigned* p, unsigned v) { return __hip_atomic_fetch_add(p, v, __ATOMIC_RELAXED, __HIP_MEMORY_SCOPE_AGENT); }
; #define XB_SPIN(cond, bar) do { unsigned _sp = 0; while (cond) { __builtin_amdgcn_s_sleep(1); \
;     if ((++_sp & 255u) == 0u) { if (xb_ld(&(bar)[XB_TMO])) break; if (_sp > XB_SPIN_CAP) { atomicAdd(&(bar)[XB_TMO], 1u); break; } } } } while (0)
; __device__ __forceinline__ void xcd_barrier(const XcdBarrier& b) {
;     ...
;         const unsigned old = xb_add(&bar[XB_XSUB(b.x)], 1u);
;         const unsigned gen = old / nloc;
;         if (old + 1u == (gen + 1u) * nloc) {
;             __builtin_amdgcn_fence(__ATOMIC_RELEASE, "agent");
;             asm volatile("s_waitcnt vmcnt(0)" ::: "memory");
;             const unsigned og = xb_add(&bar[XB_TOP], 1u);
;             const unsigned tg = og / nx;
;             if (og + 1u == (tg + 1u) * nx) xb_add(&bar[XB_TOPGEN], 1u);
;             else XB_SPIN(xb_ld(&bar[XB_TOPGEN]) == tg, bar);
;             __builtin_amdgcn_fence(__ATOMIC_ACQUIRE, "agent");
;             xb_add(&bar[XB_XGEN(b.x)], 1u);
;             asm volatile("s_waitcnt vmcnt(0)" ::: "memory");
;         } else {
;             XB_SPIN(xb_ld(&bar[XB_XGEN(b.x)]) == gen, bar);
;             __builtin_amdgcn_fence(__ATOMIC_ACQUIRE, "agent");
;             asm volatile("s_waitcnt vmcnt(0)" ::: "memory");
;         }
.LBB0_189:
	s_or_b64 exec, exec, s[16:17]
	s_waitcnt vmcnt(0)
	v_readlane_b32 s100, v244, 61
	s_cmp_lg_u32 s100, 0
	s_cbranch_scc1 .Lei_b2
	buffer_inv sc1
	s_waitcnt vmcnt(0)
.Lei_b2:
.LBB0_190:
	s_andn2_saveexec_b64 s[10:11], s[10:11]
	s_cbranch_execz .LBB0_210
	s_mov_b64 s[10:11], exec
	v_readlane_b32 s100, v244, 61
	s_cmp_lg_u32 s100, 0
	s_cbranch_scc1 .LBB0_207
	buffer_wbl2 sc1
	s_waitcnt lgkmcnt(0)
	s_waitcnt vmcnt(0)
	v_mbcnt_lo_u32_b32 v1, s10, 0
	v_mbcnt_hi_u32_b32 v1, s11, v1
	v_cmp_eq_u32_e32 vcc, 0, v1
	s_and_saveexec_b64 s[16:17], vcc
	s_cbranch_execz .LBB0_193
	s_bcnt1_i32_b64 s10, s[10:11]
	v_mov_b32_e32 v2, 0xc3000
	v_mov_b32_e32 v3, s10
	global_atomic_add v2, v2, v3, s[92:93] offset:1024 sc0

; __device__ __forceinline__ unsigned xb_ld(unsigned* p)              { return __hip_atomic_load(p, __ATOMIC_RELAXED, __HIP_MEMORY_SCOPE_AGENT); }
; #define XB_SPIN(cond, bar) do { unsigned _sp = 0; while (cond) { __builtin_amdgcn_s_sleep(1); \
;     if ((++_sp & 255u) == 0u) { if (xb_ld(&(bar)[XB_TMO])) break; if (_sp > XB_SPIN_CAP) { atomicAdd(&(bar)[XB_TMO], 1u); break; } } } } while (0)
; __device__ __forceinline__ void xcd_barrier(const XcdBarrier& b) {
;     ...
;         } else {
;             XB_SPIN(xb_ld(&bar[XB_XGEN(b.x)]) == gen, bar);
;             __builtin_amdgcn_fence(__ATOMIC_ACQUIRE, "agent");
;             asm volatile("s_waitcnt vmcnt(0)" ::: "memory");
;         }
.Lei_a3:
	v_mov_b32_e32 v0, 0x2000
	global_load_dword v0, v0, s[6:7] offset:1024 sc1
	s_add_u32 s22, s6, 0x2400
	s_addc_u32 s23, s7, 0
	s_waitcnt vmcnt(0)
	v_cmp_eq_u32_e32 vcc, v0, v1
	s_and_saveexec_b64 s[16:17], vcc
	s_cbranch_execz .LBB0_271
	s_add_u32 s20, s92, 0xc0200
	s_addc_u32 s21, s93, 0
	s_mov_b32 s36, 1
	s_mov_b64 s[24:25], 0
	v_mov_b32_e32 v0, 0
	s_branch .LBB0_262

; __device__ __forceinline__ unsigned xb_ld(unsigned* p)              { return __hip_atomic_load(p, __ATOMIC_RELAXED, __HIP_MEMORY_SCOPE_AGENT); }
; __device__ __forceinline__ unsigned xb_add(unsigned* p, unsigned v) { return __hip_atomic_fetch_add(p, v, __ATOMIC_RELAXED, __HIP_MEMORY_SCOPE_AGENT); }
; #define XB_SPIN(cond, bar) do { unsigned _sp = 0; while (cond) { __builtin_amdgcn_s_sleep(1); \
;     if ((++_sp & 255u) == 0u) { if (xb_ld(&(bar)[XB_TMO])) break; if (_sp > XB_SPIN_CAP) { atomicAdd(&(bar)[XB_TMO], 1u); break; } } } } while (0)
; __device__ __forceinline__ void xcd_barrier(const XcdBarrier& b) {
;     ...
;         unsigned nloc = b.st[0], nx = b.st[1];
;         if (nloc == 0u) { xcd_barrier_complete(bar, b.x, nloc, nx); b.st[0] = nloc; b.st[1] = nx; }
;         const unsigned old = xb_add(&bar[XB_XSUB(b.x)], 1u);
;         const unsigned gen = old / nloc;
;         if (old + 1u == (gen + 1u) * nloc) {
;             __builtin_amdgcn_fence(__ATOMIC_RELEASE, "agent");
;             asm volatile("s_waitcnt vmcnt(0)" ::: "memory");
;             const unsigned og = xb_add(&bar[XB_TOP], 1u);
;             const unsigned tg = og / nx;
;             if (og + 1u == (tg + 1u) * nx) xb_add(&bar[XB_TOPGEN], 1u);
;             else XB_SPIN(xb_ld(&bar[XB_TOPGEN]) == tg, bar);
;             __builtin_amdgcn_fence(__ATOMIC_ACQUIRE, "agent");
;             xb_add(&bar[XB_XGEN(b.x)], 1u);
;             asm volatile("s_waitcnt vmcnt(0)" ::: "memory");
;         } else {
;             XB_SPIN(xb_ld(&bar[XB_XGEN(b.x)]) == gen, bar);
;             __builtin_amdgcn_fence(__ATOMIC_ACQUIRE, "agent");
;             asm volatile("s_waitcnt vmcnt(0)" ::: "memory");
;         }
.LBB0_1118:
	s_or_b64 exec, exec, s[8:9]
	v_cvt_f32_u32_e32 v4, v2
	s_waitcnt vmcnt(0)
	v_readfirstlane_b32 s6, v3
	v_sub_u32_e32 v3, 0, v2
	v_rcp_iflag_f32_e32 v4, v4
	v_add_u32_e32 v5, s6, v1
	v_mul_f32_e32 v4, 0x4f7ffffe, v4
	v_cvt_u32_f32_e32 v4, v4
	v_mul_lo_u32 v1, v3, v4
	v_mul_hi_u32 v1, v4, v1
	v_add_u32_e32 v1, v4, v1
	v_mul_hi_u32 v1, v5, v1
	v_mul_lo_u32 v3, v1, v2
	v_sub_u32_e32 v3, v5, v3
	v_add_u32_e32 v4, 1, v1
	v_cmp_ge_u32_e32 vcc, v3, v2
	s_nop 1
	v_cndmask_b32_e32 v1, v1, v4, vcc
	v_sub_u32_e32 v4, v3, v2
	v_cndmask_b32_e32 v3, v3, v4, vcc
	v_add_u32_e32 v4, 1, v1
	v_cmp_ge_u32_e32 vcc, v3, v2
	v_add_u32_e32 v3, 1, v5
	s_nop 0
	v_cndmask_b32_e32 v1, v1, v4, vcc
	v_mul_lo_u32 v4, v2, v1
	v_add_u32_e32 v2, v4, v2
	v_cmp_ne_u32_e32 vcc, v3, v2
	s_and_saveexec_b64 s[6:7], vcc
	s_xor_b64 s[6:7], exec, s[6:7]
	s_cbranch_execz .LBB0_1132
	s_waitcnt lgkmcnt(0)
	v_readlane_b32 s100, v244, 61
	s_cmp_eq_u32 s100, 0
	s_cbranch_scc1 .Lei_a9
	buffer_inv sc1
.Lei_a9:
	v_mov_b32_e32 v0, 0x2000
	global_load_dword v0, v0, s[4:5] offset:1024 sc1
	s_add_u32 s12, s4, 0x2400
	s_addc_u32 s13, s5, 0
	s_waitcnt vmcnt(0)
	v_cmp_eq_u32_e32 vcc, v0, v1
	s_and_saveexec_b64 s[8:9], vcc
	s_cbranch_execz .LBB0_1131
	s_add_u32 s10, s92, 0xc0200
	s_addc_u32 s11, s93, 0
	s_mov_b32 s24, 1
	s_mov_b64 s[14:15], 0
	v_mov_b32_e32 v0, 0
	s_branch .LBB0_1122

; __device__ __forceinline__ unsigned xb_ld(unsigned* p)              { return __hip_atomic_load(p, __ATOMIC_RELAXED, __HIP_MEMORY_SCOPE_AGENT); }
; __device__ __forceinline__ unsigned xb_add(unsigned* p, unsigned v) { return __hip_atomic_fetch_add(p, v, __ATOMIC_RELAXED, __HIP_MEMORY_SCOPE_AGENT); }
; #define XB_SPIN(cond, bar) do { unsigned _sp = 0; while (cond) { __builtin_amdgcn_s_sleep(1); \
;     if ((++_sp & 255u) == 0u) { if (xb_ld(&(bar)[XB_TMO])) break; if (_sp > XB_SPIN_CAP) { atomicAdd(&(bar)[XB_TMO], 1u); break; } } } } while (0)
; __device__ __forceinline__ void xcd_barrier(const XcdBarrier& b) {
;     ...
;         const unsigned old = xb_add(&bar[XB_XSUB(b.x)], 1u);
;         const unsigned gen = old / nloc;
;         if (old + 1u == (gen + 1u) * nloc) {
;             __builtin_amdgcn_fence(__ATOMIC_RELEASE, "agent");
;             asm volatile("s_waitcnt vmcnt(0)" ::: "memory");
;             const unsigned og = xb_add(&bar[XB_TOP], 1u);
;             const unsigned tg = og / nx;
;             if (og + 1u == (tg + 1u) * nx) xb_add(&bar[XB_TOPGEN], 1u);
;             else XB_SPIN(xb_ld(&bar[XB_TOPGEN]) == tg, bar);
;             __builtin_amdgcn_fence(__ATOMIC_ACQUIRE, "agent");
;             xb_add(&bar[XB_XGEN(b.x)], 1u);
;             asm volatile("s_waitcnt vmcnt(0)" ::: "memory");
;         } else {
;             XB_SPIN(xb_ld(&bar[XB_XGEN(b.x)]) == gen, bar);
;             __builtin_amdgcn_fence(__ATOMIC_ACQUIRE, "agent");
;             asm volatile("s_waitcnt vmcnt(0)" ::: "memory");
;         }
.LBB0_1131:
	s_or_b64 exec, exec, s[8:9]
	s_waitcnt vmcnt(0)
	v_readlane_b32 s100, v244, 61
	s_cmp_lg_u32 s100, 0
	s_cbranch_scc1 .Lei_b9
	buffer_inv sc1
	s_waitcnt vmcnt(0)
.Lei_b9:
.LBB0_1132:
	s_andn2_saveexec_b64 s[6:7], s[6:7]
	s_cbranch_execz .LBB0_1152
	s_mov_b64 s[6:7], exec
	v_readlane_b32 s100, v244, 61
	s_cmp_lg_u32 s100, 0
	s_cbranch_scc1 .LBB0_1149
	buffer_wbl2 sc1
	s_waitcnt lgkmcnt(0)
	s_waitcnt vmcnt(0)
	v_mbcnt_lo_u32_b32 v1, s6, 0
	v_mbcnt_hi_u32_b32 v1, s7, v1
	v_cmp_eq_u32_e32 vcc, 0, v1
	s_and_saveexec_b64 s[8:9], vcc
	s_cbranch_execz .LBB0_1135
	s_bcnt1_i32_b64 s6, s[6:7]
	v_mov_b32_e32 v2, 0xc3000
	v_mov_b32_e32 v3, s6
	global_atomic_add v2, v2, v3, s[92:93] offset:1024 sc0

; __device__ __forceinline__ unsigned xb_ld(unsigned* p)              { return __hip_atomic_load(p, __ATOMIC_RELAXED, __HIP_MEMORY_SCOPE_AGENT); }
; __device__ __forceinline__ unsigned xb_add(unsigned* p, unsigned v) { return __hip_atomic_fetch_add(p, v, __ATOMIC_RELAXED, __HIP_MEMORY_SCOPE_AGENT); }
; #define XB_SPIN(cond, bar) do { unsigned _sp = 0; while (cond) { __builtin_amdgcn_s_sleep(1); \
;     if ((++_sp & 255u) == 0u) { if (xb_ld(&(bar)[XB_TMO])) break; if (_sp > XB_SPIN_CAP) { atomicAdd(&(bar)[XB_TMO], 1u); break; } } } } while (0)
; __device__ __forceinline__ void xcd_barrier(const XcdBarrier& b) {
;     ...
;         unsigned nloc = b.st[0], nx = b.st[1];
;         if (nloc == 0u) { xcd_barrier_complete(bar, b.x, nloc, nx); b.st[0] = nloc; b.st[1] = nx; }
;         const unsigned old = xb_add(&bar[XB_XSUB(b.x)], 1u);
;         const unsigned gen = old / nloc;
;         if (old + 1u == (gen + 1u) * nloc) {
;             __builtin_amdgcn_fence(__ATOMIC_RELEASE, "agent");
;             asm volatile("s_waitcnt vmcnt(0)" ::: "memory");
;             const unsigned og = xb_add(&bar[XB_TOP], 1u);
;             const unsigned tg = og / nx;
;             if (og + 1u == (tg + 1u) * nx) xb_add(&bar[XB_TOPGEN], 1u);
;             else XB_SPIN(xb_ld(&bar[XB_TOPGEN]) == tg, bar);
;             __builtin_amdgcn_fence(__ATOMIC_ACQUIRE, "agent");
;             xb_add(&bar[XB_XGEN(b.x)], 1u);
;             asm volatile("s_waitcnt vmcnt(0)" ::: "memory");
;         } else {
;             XB_SPIN(xb_ld(&bar[XB_XGEN(b.x)]) == gen, bar);
;             __builtin_amdgcn_fence(__ATOMIC_ACQUIRE, "agent");
;             asm volatile("s_waitcnt vmcnt(0)" ::: "memory");
;         }
.LBB0_1267:
	s_or_b64 exec, exec, s[10:11]
	v_cvt_f32_u32_e32 v4, v2
	s_waitcnt vmcnt(0)
	v_readfirstlane_b32 s8, v3
	v_sub_u32_e32 v3, 0, v2
	v_rcp_iflag_f32_e32 v4, v4
	v_add_u32_e32 v5, s8, v1
	v_mul_f32_e32 v4, 0x4f7ffffe, v4
	v_cvt_u32_f32_e32 v4, v4
	v_mul_lo_u32 v1, v3, v4
	v_mul_hi_u32 v1, v4, v1
	v_add_u32_e32 v1, v4, v1
	v_mul_hi_u32 v1, v5, v1
	v_mul_lo_u32 v3, v1, v2
	v_sub_u32_e32 v3, v5, v3
	v_add_u32_e32 v4, 1, v1
	v_cmp_ge_u32_e32 vcc, v3, v2
	s_nop 1
	v_cndmask_b32_e32 v1, v1, v4, vcc
	v_sub_u32_e32 v4, v3, v2
	v_cndmask_b32_e32 v3, v3, v4, vcc
	v_add_u32_e32 v4, 1, v1
	v_cmp_ge_u32_e32 vcc, v3, v2
	v_add_u32_e32 v3, 1, v5
	s_nop 0
	v_cndmask_b32_e32 v1, v1, v4, vcc
	v_mul_lo_u32 v4, v2, v1
	v_add_u32_e32 v2, v4, v2
	v_cmp_ne_u32_e32 vcc, v3, v2
	s_and_saveexec_b64 s[8:9], vcc
	s_xor_b64 s[8:9], exec, s[8:9]
	s_cbranch_execz .LBB0_1281
	s_waitcnt lgkmcnt(0)
	v_readlane_b32 s100, v244, 61
	s_cmp_eq_u32 s100, 0
	s_cbranch_scc1 .Lei_a11
	buffer_inv sc1
.Lei_a11:
	v_mov_b32_e32 v0, 0x2000
	global_load_dword v0, v0, s[6:7] offset:1024 sc1
	s_add_u32 s14, s6, 0x2400
	s_addc_u32 s15, s7, 0
	s_waitcnt vmcnt(0)
	v_cmp_eq_u32_e32 vcc, v0, v1
	s_and_saveexec_b64 s[10:11], vcc
	s_cbranch_execz .LBB0_1280
	s_add_u32 s12, s92, 0xc0200
	s_addc_u32 s13, s93, 0
	s_mov_b32 s26, 1
	s_mov_b64 s[16:17], 0
	v_mov_b32_e32 v0, 0
	s_branch .LBB0_1271

; __device__ __forceinline__ unsigned xb_ld(unsigned* p)              { return __hip_atomic_load(p, __ATOMIC_RELAXED, __HIP_MEMORY_SCOPE_AGENT); }
; __device__ __forceinline__ unsigned xb_add(unsigned* p, unsigned v) { return __hip_atomic_fetch_add(p, v, __ATOMIC_RELAXED, __HIP_MEMORY_SCOPE_AGENT); }
; #define XB_SPIN(cond, bar) do { unsigned _sp = 0; while (cond) { __builtin_amdgcn_s_sleep(1); \
;     if ((++_sp & 255u) == 0u) { if (xb_ld(&(bar)[XB_TMO])) break; if (_sp > XB_SPIN_CAP) { atomicAdd(&(bar)[XB_TMO], 1u); break; } } } } while (0)
; __device__ __forceinline__ void xcd_barrier(const XcdBarrier& b) {
;     ...
;         const unsigned old = xb_add(&bar[XB_XSUB(b.x)], 1u);
;         const unsigned gen = old / nloc;
;         if (old + 1u == (gen + 1u) * nloc) {
;             __builtin_amdgcn_fence(__ATOMIC_RELEASE, "agent");
;             asm volatile("s_waitcnt vmcnt(0)" ::: "memory");
;             const unsigned og = xb_add(&bar[XB_TOP], 1u);
;             const unsigned tg = og / nx;
;             if (og + 1u == (tg + 1u) * nx) xb_add(&bar[XB_TOPGEN], 1u);
;             else XB_SPIN(xb_ld(&bar[XB_TOPGEN]) == tg, bar);
;             __builtin_amdgcn_fence(__ATOMIC_ACQUIRE, "agent");
;             xb_add(&bar[XB_XGEN(b.x)], 1u);
.Lei_b11:
.LBB0_1281:
	s_andn2_saveexec_b64 s[8:9], s[8:9]
	s_cbranch_execz .LBB0_1301
	s_mov_b64 s[8:9], exec
	v_readlane_b32 s100, v244, 61
	s_cmp_lg_u32 s100, 0
	s_cbranch_scc1 .LBB0_1298
	buffer_wbl2 sc1
	s_waitcnt lgkmcnt(0)
	s_waitcnt vmcnt(0)
	v_mbcnt_lo_u32_b32 v1, s8, 0
	v_mbcnt_hi_u32_b32 v1, s9, v1
	v_cmp_eq_u32_e32 vcc, 0, v1
	s_and_saveexec_b64 s[10:11], vcc
	s_cbranch_execz .LBB0_1284
	s_bcnt1_i32_b64 s8, s[8:9]
	v_mov_b32_e32 v2, 0xc3000
	v_mov_b32_e32 v3, s8
	global_atomic_add v2, v2, v3, s[92:93] offset:1024 sc0

; __device__ __forceinline__ unsigned xb_ld(unsigned* p)              { return __hip_atomic_load(p, __ATOMIC_RELAXED, __HIP_MEMORY_SCOPE_AGENT); }
; #define XB_SPIN(cond, bar) do { unsigned _sp = 0; while (cond) { __builtin_amdgcn_s_sleep(1); \
;     if ((++_sp & 255u) == 0u) { if (xb_ld(&(bar)[XB_TMO])) break; if (_sp > XB_SPIN_CAP) { atomicAdd(&(bar)[XB_TMO], 1u); break; } } } } while (0)
; __device__ __forceinline__ void xcd_barrier(const XcdBarrier& b) {
;     ...
;         } else {
;             XB_SPIN(xb_ld(&bar[XB_XGEN(b.x)]) == gen, bar);
;             __builtin_amdgcn_fence(__ATOMIC_ACQUIRE, "agent");
;             asm volatile("s_waitcnt vmcnt(0)" ::: "memory");
;         }
.Lei_a12:
	v_mov_b32_e32 v0, 0x2000
	global_load_dword v0, v0, s[2:3] offset:1024 sc1
	s_add_u32 s12, s2, 0x2400
	s_addc_u32 s13, s3, 0
	s_waitcnt vmcnt(0)
	v_cmp_eq_u32_e32 vcc, v0, v1
	s_and_saveexec_b64 s[8:9], vcc
	s_cbranch_execz .LBB0_1350
	s_add_u32 s10, s92, 0xc0200
	s_addc_u32 s11, s93, 0
	s_mov_b32 s24, 1
	s_mov_b64 s[14:15], 0
	v_mov_b32_e32 v0, 0
	s_branch .LBB0_1341
